# v022 + cross QK K-fragment reads pipelined 6 deep + z-gate tile cache-touch (one lane-strided global_load_dword per wave) before the attention and cross-attention epilogues
# speedup vs baseline: 1.0154x; 1.0062x over previous
; DI float bf2f(unsigned short u) { return __uint_as_float((unsigned)u << 16); }
; DI unsigned f2bf(float f) { unsigned u = __float_as_uint(f); return (u + 0x7fffu + ((u >> 16) & 1u)) >> 16; }
; DI void attn_unit(Ctx A_, LAS unsigned char* lds, int b, int h, int qb, float lam, int wave, int lane) {
;     ...
;     l += __shfl_xor(l, 32);
;     if (hh == 0) wsf[32 + r] = l;
;     ...
;                 Y_[rw * YLD + C_YA + h_e * 128 + nb * 32 + r_e] = (bf16)f2bf(o[nb][i] * ssq[i] * sn * bf2f(P[rw * PLD + C_ZA + h_e * 128 + nb * 32 + r_e]));
.LBB0_890:
	s_or_b32 s98, s64, s0
	s_mul_hi_u32 s99, s98, 0x5800
	s_mul_i32 s98, s98, 0x5800
	v_readlane_b32 s100, v255, 9
	v_readlane_b32 s101, v255, 10
	v_and_b32_e32 v206, 63, v0
	v_lshrrev_b32_e32 v207, 1, v206
	s_add_u32 s98, s98, s100
	s_addc_u32 s99, s99, s101
	s_lshl_b32 s100, s63, 8
	s_addk_i32 s100, 0x1800
	s_add_u32 s98, s98, s100
	s_addc_u32 s99, s99, 0
	v_mul_u32_u24_e32 v207, 0x5800, v207
	v_and_b32_e32 v206, 1, v206
	v_lshl_or_b32 v206, v206, 7, v207
	s_nop 0
	global_load_dword v207, v206, s[98:99]
	ds_bpermute_b32 v66, v204, v218
	s_and_saveexec_b64 s[4:5], s[8:9]
	s_cbranch_execz .LBB0_892
	s_waitcnt lgkmcnt(0)
	v_add_f32_e32 v66, v218, v66
	v_lshl_add_u32 v67, v214, 2, s40
	ds_write_b32 v67, v66 offset:128

; #define LAS __attribute__((address_space(3)))
; DI int tid_now() { int t; asm volatile("v_mov_b32 %0, %1" : "=v"(t) : "v"((int)threadIdx.x)); return t; }
; #define Q_NEXT(k, id) do { if (tid == 0) qw[qit & 1] = __hip_atomic_fetch_add(qctr + 64 * (k), 1u, __ATOMIC_RELAXED, __HIP_MEMORY_SCOPE_AGENT); __syncthreads(); \
;         id = __builtin_amdgcn_readfirstlane((int)qw[qit & 1]); ++qit; } while (0)
; DI void cross_unit(Ctx A_, LAS unsigned char* lds, int kvb, int hc, size_t row0, int nrows, int wave, int lane) {
;     const int r = lane & 31, hh = lane >> 5, rg = wave & 3, dvh = wave >> 2;
;     bf16* P = P_;
;     const bf16* Kg = MKV_ + (size_t)kvb * NMEM * 2048 + hc * 256; const bf16* Vg = Kg + 1024;
;     LAS float* wsf = (LAS float*)(lds + WSF_OFF) + wave * 128;
;     const bool act = rg * 32 < nrows;
;     load_tile(lds, Kg, Vg, 0, wave, lane);
;     bf16x8 qr[16];
;     { const bf16* Qg = P + (row0 + rg * 32 + r) * PLD + C_QC + hc * 256 + hh * 8;
; #pragma unroll
;       for (int d0 = 0; d0 < 16; ++d0) qr[d0] = *(const bf16x8*)(Qg + d0 * 16); }
;     asm volatile("" : "+v"(qr[0]), "+v"(qr[1]), "+v"(qr[2]), "+v"(qr[3]), "+v"(qr[4]), "+v"(qr[5]), "+v"(qr[6]), "+v"(qr[7]), "+v"(qr[8]), "+v"(qr[9]), "+v"(qr[10]), "+v"(qr[11]), "+v"(qr[12]), "+v"(qr[13]), "+v"(qr[14]), "+v"(qr[15]));
;     f32x16 o[4];
; #pragma unroll
;     for (int nb = 0; nb < 4; ++nb)
; #pragma unroll
;         for (int i = 0; i < 16; ++i) o[nb][i] = 0.f;
;     float m = -INFINITY, l = 0.f;
;     const int g16 = (lane >> 4) & 1, p4 = lane & 3, q4 = (lane & 15) >> 2;
; __global__ void __launch_bounds__(512, 2) fwd(Args args) {
;     ...
;         for (;;) { int id; Q_NEXT(3, id); if (id >= 1152) break; const int lane = tid_now() & 63;
;             if (id < 1024) { const int qb = id & 31, hc = (id >> 5) & 3, b = id >> 7; ca::cross_unit(A_, lds, b, hc, (size_t)b * SEQ + qb * 128, 128, wave, lane); }
;             else { const int sidx = id - 1024, hc = sidx & 3, b = sidx >> 2; ca::cross_unit(A_, lds, 8 + b, hc, (size_t)MP + b * DS, DS, wave, lane); } }
.LBB0_904:
	s_or_b64 exec, exec, s[4:5]
	s_lshl_b32 s2, s2, 2
	s_add_i32 s2, s2, 0
	s_add_i32 s2, s2, 0x20040
	v_mov_b32_e32 v2, s2
	s_waitcnt lgkmcnt(0)
	s_barrier
	ds_read_b32 v2, v2
	s_mov_b64 s[4:5], -1
	s_waitcnt lgkmcnt(0)
	v_readfirstlane_b32 s63, v2
	s_mov_b32 s101, s63
	s_cmpk_gt_i32 s63, 0x47f
	s_cbranch_scc1 .LBB0_899
	v_mov_b32 v2, v0
	s_mov_b64 s[30:31], -1
	v_and_b32_e32 v175, 63, v2
	v_and_b32_e32 v164, 31, v2
	v_lshrrev_b32_e32 v174, 5, v175
	v_lshrrev_b32_e32 v4, 2, v175
	v_lshlrev_b32_e32 v5, 3, v175
	v_lshlrev_b32_e32 v6, 1, v175
	v_lshlrev_b32_e32 v7, 4, v175
	v_and_b32_e32 v172, 60, v2
	v_and_b32_e32 v2, 3, v2
	s_cmpk_gt_i32 s63, 0x3ff
	v_cmp_gt_u32_e64 s[4:5], 32, v175
	v_lshlrev_b32_e32 v166, 12, v164
	s_waitcnt vmcnt(0)
	v_and_b32_e32 v158, 8, v4
	v_and_b32_e32 v176, 24, v5
	v_lshlrev_b32_e32 v148, 12, v4
	v_lshlrev_b32_e32 v162, 4, v174
	v_lshlrev_b32_e32 v177, 9, v174
	v_lshlrev_b32_e32 v178, 4, v164
	v_lshl_add_u32 v179, v164, 2, s40
	v_and_b32_e32 v180, 32, v6
	v_lshlrev_b32_e32 v181, 8, v174
	v_and_b32_e32 v182, 0xc0, v7
	v_lshlrev_b32_e32 v173, 4, v2
	s_cbranch_scc0 .LBB0_924
	s_add_i32 s2, s63, 0xfffffc00
	s_lshr_b32 s30, s2, 2
	s_add_i32 s2, s30, 8
	s_lshl_b32 s34, s30, 4
	s_add_i32 s34, s34, 0x8000
	s_lshl_b64 s[64:65], s[2:3], 20
	s_add_u32 s31, s42, s64
	s_addc_u32 s65, s43, s65
	s_lshl_b32 s2, s63, 8
	s_and_b32 s35, s2, 0x300
	s_lshl_b32 s2, s35, 1
	s_add_u32 s64, s31, s2
	s_addc_u32 s65, s65, 0
	v_mov_b32_e32 v167, v3
	v_or_b32_e32 v150, s80, v158
	v_or_b32_e32 v152, s45, v158
	v_lshl_add_u64 v[4:5], s[64:65], 0, v[166:167]
	v_ashrrev_i32_e32 v151, 31, v150
	v_ashrrev_i32_e32 v153, 31, v152
	s_add_u32 s64, s64, s8
	v_lshl_add_u64 v[6:7], v[150:151], 1, v[4:5]
	s_mov_b32 s31, m0
	s_mov_b32 m0, s37
	s_nop 0
	global_load_lds_dwordx4 v[6:7], off
	s_mov_b32 m0, s31
	v_lshl_add_u64 v[4:5], v[152:153], 1, v[4:5]
	s_addc_u32 s65, s65, s9
	v_lshlrev_b32_e32 v2, 1, v176
	s_mov_b32 s31, m0
	s_mov_b32 m0, s39
	s_nop 0
	global_load_lds_dwordx4 v[4:5], off
	s_mov_b32 m0, s31
	v_lshl_add_u64 v[4:5], s[64:65], 0, v[2:3]
	v_mov_b32_e32 v149, v3
	v_lshl_add_u64 v[4:5], v[4:5], 0, v[148:149]
	v_lshl_add_u64 v[6:7], v[4:5], 0, s[14:15]
	s_mov_b32 s31, m0
	s_mov_b32 m0, s47
	s_nop 0
	global_load_lds_dwordx4 v[6:7], off
	s_mov_b32 m0, s31
	v_lshl_add_u64 v[4:5], v[4:5], 0, s[16:17]
	s_mov_b32 s31, m0
	s_mov_b32 m0, s48
	s_nop 0
	global_load_lds_dwordx4 v[4:5], off
	s_mov_b32 m0, s31
	v_readlane_b32 s64, v255, 9
	s_add_i32 s31, s34, s44
	v_readlane_b32 s65, v255, 10
	v_add_u32_e32 v2, s31, v164
	v_mov_b32_e32 v163, v3
	v_mov_b64_e32 v[4:5], s[64:65]
	v_mad_u64_u32 v[4:5], s[64:65], v2, s59, v[4:5]
	v_lshl_add_u64 v[4:5], v[4:5], 0, s[2:3]
	v_lshl_add_u64 v[4:5], v[4:5], 0, v[162:163]
	v_lshl_add_u64 v[6:7], v[4:5], 0, s[18:19]
	v_add_co_u32_e32 v4, vcc, s46, v4
	s_mov_b32 s31, s3
	s_nop 0
	v_addc_co_u32_e32 v5, vcc, 0, v5, vcc
	global_load_dwordx4 v[84:87], v[4:5], off offset:2048
	global_load_dwordx4 v[88:91], v[6:7], off offset:480
	global_load_dwordx4 v[92:95], v[6:7], off offset:448
	global_load_dwordx4 v[96:99], v[6:7], off offset:416
	global_load_dwordx4 v[100:103], v[6:7], off offset:384
	global_load_dwordx4 v[104:107], v[6:7], off offset:352
	global_load_dwordx4 v[108:111], v[6:7], off offset:320
	global_load_dwordx4 v[112:115], v[6:7], off offset:288
	global_load_dwordx4 v[116:119], v[6:7], off offset:256
	global_load_dwordx4 v[120:123], v[6:7], off offset:224
	global_load_dwordx4 v[124:127], v[6:7], off offset:192
	global_load_dwordx4 v[128:131], v[6:7], off offset:160
	global_load_dwordx4 v[132:135], v[6:7], off offset:128
	global_load_dwordx4 v[136:139], v[6:7], off offset:96
	global_load_dwordx4 v[140:143], v[6:7], off offset:64
	global_load_dwordx4 v[144:147], v[6:7], off offset:32
	s_lshl_b64 s[30:31], s[30:31], 20
	s_lshl_b32 s64, s63, 9
	v_lshl_or_b32 v18, v172, 10, s30
	s_and_b32 s64, s64, 0x600
	v_or3_b32 v18, v18, s64, v173
	s_add_u32 s64, s55, s64
	v_mov_b32_e32 v16, v3
	v_mov_b32_e32 v17, v3
	s_addc_u32 s65, s56, 0
	v_mov_b32_e32 v4, v3
	v_mov_b32_e32 v5, v3
	v_mov_b32_e32 v6, v3
	v_mov_b32_e32 v7, v3
	v_mov_b32_e32 v8, v3
	v_mov_b32_e32 v9, v3
	v_mov_b32_e32 v10, v3
	v_mov_b32_e32 v11, v3
	v_mov_b32_e32 v12, v3
	v_mov_b32_e32 v13, v3
	v_mov_b32_e32 v14, v3
	v_mov_b32_e32 v15, v3
	v_mov_b32_e32 v19, s31
	v_mov_b32_e32 v2, v3
	v_mov_b64_e32 v[66:67], v[16:17]
	v_mov_b64_e32 v[50:51], v[16:17]
	v_mov_b64_e32 v[34:35], v[16:17]
	s_add_u32 s30, s64, s30
	v_mov_b64_e32 v[64:65], v[14:15]
	v_mov_b64_e32 v[62:63], v[12:13]
	v_mov_b64_e32 v[60:61], v[10:11]
	v_mov_b64_e32 v[58:59], v[8:9]
	v_mov_b64_e32 v[56:57], v[6:7]
	v_mov_b64_e32 v[54:55], v[4:5]
	v_mov_b64_e32 v[52:53], v[2:3]
	v_mov_b64_e32 v[48:49], v[14:15]
	v_mov_b64_e32 v[46:47], v[12:13]
	v_mov_b64_e32 v[44:45], v[10:11]
	v_mov_b64_e32 v[42:43], v[8:9]
	v_mov_b64_e32 v[40:41], v[6:7]
	v_mov_b64_e32 v[38:39], v[4:5]
	v_mov_b64_e32 v[36:37], v[2:3]
	v_mov_b64_e32 v[32:33], v[14:15]
	v_mov_b64_e32 v[30:31], v[12:13]
	v_mov_b64_e32 v[28:29], v[10:11]
	v_mov_b64_e32 v[26:27], v[8:9]
	v_mov_b64_e32 v[24:25], v[6:7]
	v_mov_b64_e32 v[22:23], v[4:5]
	v_mov_b64_e32 v[20:21], v[2:3]
	v_lshl_add_u64 v[154:155], s[10:11], 0, v[18:19]
	s_addc_u32 s31, s65, s31
	v_mov_b64_e32 v[18:19], v[16:17]
	s_mov_b32 s2, 0
	v_mov_b32_e32 v149, 0
	v_mov_b32_e32 v159, 0xff800000
	v_lshl_add_u64 v[156:157], s[30:31], 0, v[166:167]
	v_mov_b64_e32 v[16:17], v[14:15]
	v_mov_b64_e32 v[14:15], v[12:13]
	v_mov_b64_e32 v[12:13], v[10:11]
	v_mov_b64_e32 v[10:11], v[8:9]
	v_mov_b64_e32 v[8:9], v[6:7]
	v_mov_b64_e32 v[6:7], v[4:5]
	v_mov_b64_e32 v[4:5], v[2:3]
	s_waitcnt vmcnt(0)
; DI float bf2f(unsigned short u) { return __uint_as_float((unsigned)u << 16); }
; DI unsigned f2bf(float f) { unsigned u = __float_as_uint(f); return (u + 0x7fffu + ((u >> 16) & 1u)) >> 16; }
; DI void cross_unit(Ctx A_, LAS unsigned char* lds, int kvb, int hc, size_t row0, int nrows, int wave, int lane) {
;     ...
;         asm volatile("s_waitcnt vmcnt(0) lgkmcnt(0)" ::: "memory"); __builtin_amdgcn_s_barrier(); asm volatile("" ::: "memory");
;         if (t + 1 < 8) load_tile(lds + ((t + 1) & 1) * BUF, Kg, Vg, (t + 1) * 32, wave, lane);
;     ...
;                 if (q < nrows) { const size_t eo = (row0 + q) * PLD + hc * 256 + dvh * 128 + nb * 32 + r; Y_[(row0 + q) * YLD + C_YC + hc * 256 + dvh * 128 + nb * 32 + r] = (bf16)f2bf(o[nb][i] * rl[i] * bf2f(P[eo + C_ZC])); }
.LBB0_907:
	s_waitcnt vmcnt(0) lgkmcnt(0)
	s_barrier
	s_cmp_eq_u32 s2, 0x38000
	s_cbranch_scc1 .Lcross_touch_p
	s_add_i32 s30, s2, 0x8000
	s_and_b32 s30, s30, 0x8000
	s_add_i32 s30, s30, 0
	v_lshl_add_u64 v[68:69], v[150:151], 1, v[156:157]
	s_add_i32 s31, s30, s33
	s_mov_b32 s64, m0
	s_mov_b32 m0, s31
	s_nop 0
	global_load_lds_dwordx4 v[68:69], off
	s_mov_b32 m0, s64
	v_lshl_add_u64 v[68:69], v[152:153], 1, v[156:157]
	s_add_i32 s30, s30, s38
	s_mov_b32 s64, m0
	s_mov_b32 m0, s30
	s_nop 0
	global_load_lds_dwordx4 v[68:69], off
	s_mov_b32 m0, s64
	s_add_i32 s30, s31, 0x4000
	s_mov_b32 s64, m0
	s_mov_b32 m0, s30
	s_nop 0
	global_load_lds_dwordx4 v[154:155], off
	s_mov_b32 m0, s64
	v_lshl_add_u64 v[68:69], v[154:155], 0, s[20:21]
	s_add_i32 s30, s31, 0x4400
	s_mov_b32 s31, m0
	s_mov_b32 m0, s30
	s_nop 0
	global_load_lds_dwordx4 v[68:69], off
	s_mov_b32 m0, s31
	s_branch .LBB0_909
.Lcross_touch_p:
	s_cmpk_gt_i32 s101, 0x3ff
	s_cbranch_scc1 .LctS_p
	s_lshr_b32 s98, s101, 7
	s_lshl_b32 s98, s98, 12
	s_and_b32 s99, s101, 31
	s_lshl_b32 s99, s99, 7
	s_add_i32 s98, s98, s99
	s_bfe_u32 s100, s101, 0x20005
	s_branch .LctC_p
.LctS_p:
	s_add_i32 s99, s101, 0xfffffc00
	s_lshr_b32 s98, s99, 2
	s_lshl_b32 s98, s98, 4
	s_add_i32 s98, s98, 0x8000
	s_and_b32 s100, s99, 3
.LctC_p:
	v_readfirstlane_b32 vcc_lo, v0
	s_lshr_b32 vcc_lo, vcc_lo, 6
	s_and_b32 vcc_hi, vcc_lo, 3
	s_lshl_b32 vcc_hi, vcc_hi, 5
	s_add_i32 s98, s98, vcc_hi
	s_lshr_b32 vcc_lo, vcc_lo, 2
	s_lshl_b32 vcc_lo, vcc_lo, 8
	s_lshl_b32 s100, s100, 9
	s_add_i32 s100, s100, vcc_lo
	s_add_i32 s100, s100, 0x5000
	s_mul_hi_u32 s99, s98, 0x5800
	s_mul_i32 s98, s98, 0x5800
	v_readlane_b32 vcc_lo, v255, 9
	v_readlane_b32 vcc_hi, v255, 10
	v_and_b32_e32 v206, 63, v0
	v_lshrrev_b32_e32 v207, 1, v206
	s_add_u32 s98, s98, vcc_lo
	s_addc_u32 s99, s99, vcc_hi
	s_add_u32 s98, s98, s100
	s_addc_u32 s99, s99, 0
	v_mul_u32_u24_e32 v207, 0x5800, v207
	v_and_b32_e32 v206, 1, v206
	v_lshl_or_b32 v206, v206, 7, v207
	s_nop 0
	global_load_dword v207, v206, s[98:99]

; #define LAS __attribute__((address_space(3)))
; DI float fexp2(float x) { return __builtin_amdgcn_exp2f(x); }
; DI int crow(int i, int hh) { return (i & 3) + 8 * (i >> 2) + 4 * hh; }
; DI void cross_unit(Ctx A_, LAS unsigned char* lds, int kvb, int hc, size_t row0, int nrows, int wave, int lane) {
;     ...
;             const LAS unsigned char* buf = lds + (t & 1) * BUF;
;             const LAS unsigned char* kb = buf + hh * 512 + r * 16;
;             f32x16 p0;
; #pragma unroll
;             for (int i = 0; i < 16; ++i) p0[i] = 0.f;
; #pragma unroll
;             for (int d0 = 0; d0 < 16; ++d0) p0 = __builtin_amdgcn_mfma_f32_32x32x16_bf16(*(const LAS bf16x8*)(kb + d0 * 1024), qr[d0], p0, 0, 0, 0);
;             float tm = p0[0];
; #pragma unroll
;             for (int i = 1; i < 16; ++i) tm = fmaxf(tm, p0[i]);
;             tm = fmaxf(tm, __shfl_xor(tm, 32));
;             if (__any(tm > m + RESC_THR)) {
;                 const float mn = fmaxf(m, tm), f = fexp2(m - mn); m = mn; l *= f;
;                 if (hh == 0) wsf[r] = f;
;                 float fr[16];
; #pragma unroll
;                 for (int i = 0; i < 16; ++i) fr[i] = wsf[crow(i, hh)];
; #pragma unroll
;                 for (int nb = 0; nb < 4; ++nb)
; #pragma unroll
;                     for (int i = 0; i < 16; ++i) o[nb][i] *= fr[i];
;             }
.LBB0_911:
	s_and_b32 s30, s2, 0x8000
	s_add_i32 s64, s30, 0
	v_add3_u32 v2, s64, v177, v178
	ds_read_b128 v[168:171], v2
	ds_read_b128 v[184:187], v2 offset:1024
	ds_read_b128 v[236:239], v2 offset:2048
	ds_read_b128 v[240:243], v2 offset:3072
	ds_read_b128 v[244:247], v2 offset:4096
	ds_read_b128 v[248:251], v2 offset:5120
	s_waitcnt lgkmcnt(5)
	v_mfma_f32_32x32x16_bf16 v[68:83], v[168:171], v[84:87], 0
	ds_read_b128 v[168:171], v2 offset:6144
	s_waitcnt lgkmcnt(5)
	v_mfma_f32_32x32x16_bf16 v[68:83], v[184:187], v[144:147], v[68:83]
	ds_read_b128 v[184:187], v2 offset:7168
	s_waitcnt lgkmcnt(5)
	v_mfma_f32_32x32x16_bf16 v[68:83], v[236:239], v[140:143], v[68:83]
	ds_read_b128 v[236:239], v2 offset:8192
	s_waitcnt lgkmcnt(5)
	v_mfma_f32_32x32x16_bf16 v[68:83], v[240:243], v[136:139], v[68:83]
	ds_read_b128 v[240:243], v2 offset:9216
	s_waitcnt lgkmcnt(5)
	v_mfma_f32_32x32x16_bf16 v[68:83], v[244:247], v[132:135], v[68:83]
	ds_read_b128 v[244:247], v2 offset:10240
	s_waitcnt lgkmcnt(5)
	v_mfma_f32_32x32x16_bf16 v[68:83], v[248:251], v[128:131], v[68:83]
	ds_read_b128 v[248:251], v2 offset:11264
	s_waitcnt lgkmcnt(5)
	v_mfma_f32_32x32x16_bf16 v[68:83], v[168:171], v[124:127], v[68:83]
	ds_read_b128 v[168:171], v2 offset:12288
	s_waitcnt lgkmcnt(5)
	v_mfma_f32_32x32x16_bf16 v[68:83], v[184:187], v[120:123], v[68:83]
	ds_read_b128 v[184:187], v2 offset:13312
	s_waitcnt lgkmcnt(5)
	v_mfma_f32_32x32x16_bf16 v[68:83], v[236:239], v[116:119], v[68:83]
	ds_read_b128 v[236:239], v2 offset:14336
	s_waitcnt lgkmcnt(5)
	v_mfma_f32_32x32x16_bf16 v[68:83], v[240:243], v[112:115], v[68:83]
	ds_read_b128 v[240:243], v2 offset:15360
	s_waitcnt lgkmcnt(5)
	v_mfma_f32_32x32x16_bf16 v[68:83], v[244:247], v[108:111], v[68:83]
	s_waitcnt lgkmcnt(4)
	v_mfma_f32_32x32x16_bf16 v[68:83], v[248:251], v[104:107], v[68:83]
	s_waitcnt lgkmcnt(3)
	v_mfma_f32_32x32x16_bf16 v[68:83], v[168:171], v[100:103], v[68:83]
	s_waitcnt lgkmcnt(2)
	v_mfma_f32_32x32x16_bf16 v[68:83], v[184:187], v[96:99], v[68:83]
	s_waitcnt lgkmcnt(1)
	v_mfma_f32_32x32x16_bf16 v[68:83], v[236:239], v[92:95], v[68:83]
	s_waitcnt lgkmcnt(0)
	v_mfma_f32_32x32x16_bf16 v[68:83], v[240:243], v[88:91], v[68:83]
	s_nop 11
	v_max_f32_e32 v2, v69, v69
	v_max_f32_e32 v160, v68, v68
	v_max_f32_e32 v2, v160, v2
	v_max3_f32 v2, v2, v70, v71
	v_max3_f32 v2, v2, v72, v73
	v_max3_f32 v2, v2, v74, v75
	v_max3_f32 v2, v2, v76, v77
	v_max3_f32 v2, v2, v78, v79
	v_max3_f32 v2, v2, v80, v81
	v_max3_f32 v2, v2, v82, v83
	ds_bpermute_b32 v160, v204, v2
	s_waitcnt lgkmcnt(0)
	v_max_f32_e32 v160, v160, v160
	v_max_f32_e32 v2, v2, v160
	v_add_f32_e32 v160, 0x41000000, v159
	v_cmp_gt_f32_e32 vcc, v2, v160
	s_cbranch_vccz .LBB0_915
	v_max_f32_e32 v2, v2, v2
	v_max_f32_e32 v160, v159, v159
	v_max_f32_e32 v2, v160, v2
	v_sub_f32_e32 v159, v159, v2
	v_exp_f32_e32 v159, v159
	s_and_saveexec_b64 s[30:31], s[4:5]
	ds_write_b32 v179, v159
	s_or_b64 exec, exec, s[30:31]
	v_add_u32_e32 v160, s40, v162
	ds_read_b128 v[168:171], v160 offset:96
	ds_read_b128 v[184:187], v160 offset:64
	ds_read_b128 v[188:191], v160 offset:32
	ds_read_b128 v[192:195], v160
	v_mul_f32_e32 v149, v149, v159
	s_waitcnt lgkmcnt(3)
	v_pk_mul_f32 v[64:65], v[64:65], v[168:169]
	s_waitcnt lgkmcnt(2)
	v_pk_mul_f32 v[60:61], v[60:61], v[184:185]
	s_waitcnt lgkmcnt(1)
	v_pk_mul_f32 v[56:57], v[56:57], v[188:189]
	v_pk_mul_f32 v[66:67], v[66:67], v[170:171]
	v_pk_mul_f32 v[62:63], v[62:63], v[186:187]
	v_pk_mul_f32 v[58:59], v[58:59], v[190:191]
	s_waitcnt lgkmcnt(0)
	v_pk_mul_f32 v[54:55], v[54:55], v[194:195]
	v_pk_mul_f32 v[52:53], v[52:53], v[192:193]
	v_pk_mul_f32 v[48:49], v[48:49], v[168:169]
	v_pk_mul_f32 v[44:45], v[44:45], v[184:185]
	v_pk_mul_f32 v[40:41], v[40:41], v[188:189]
	v_pk_mul_f32 v[50:51], v[50:51], v[170:171]
	v_pk_mul_f32 v[46:47], v[46:47], v[186:187]
	v_pk_mul_f32 v[42:43], v[42:43], v[190:191]
	v_pk_mul_f32 v[38:39], v[38:39], v[194:195]
	v_pk_mul_f32 v[36:37], v[36:37], v[192:193]
	v_pk_mul_f32 v[32:33], v[32:33], v[168:169]
	v_pk_mul_f32 v[28:29], v[28:29], v[184:185]
	v_pk_mul_f32 v[24:25], v[24:25], v[188:189]
	v_pk_mul_f32 v[34:35], v[34:35], v[170:171]
	v_pk_mul_f32 v[30:31], v[30:31], v[186:187]
	v_pk_mul_f32 v[26:27], v[26:27], v[190:191]
	v_pk_mul_f32 v[22:23], v[22:23], v[194:195]
	v_pk_mul_f32 v[20:21], v[20:21], v[192:193]
	v_pk_mul_f32 v[16:17], v[16:17], v[168:169]
	v_pk_mul_f32 v[12:13], v[12:13], v[184:185]
	v_pk_mul_f32 v[8:9], v[8:9], v[188:189]
	v_pk_mul_f32 v[18:19], v[18:19], v[170:171]
	v_pk_mul_f32 v[14:15], v[14:15], v[186:187]
	v_pk_mul_f32 v[10:11], v[10:11], v[190:191]
	v_pk_mul_f32 v[6:7], v[6:7], v[194:195]
	v_pk_mul_f32 v[4:5], v[4:5], v[192:193]
	s_branch .LBB0_916

; DI void cross_unit(Ctx A_, LAS unsigned char* lds, int kvb, int hc, size_t row0, int nrows, int wave, int lane) {
;     ...
;         asm volatile("s_waitcnt vmcnt(0) lgkmcnt(0)" ::: "memory"); __builtin_amdgcn_s_barrier(); asm volatile("" ::: "memory");
;         if (t + 1 < 8) load_tile(lds + ((t + 1) & 1) * BUF, Kg, Vg, (t + 1) * 32, wave, lane);
.LBB0_926:
	s_waitcnt vmcnt(0) lgkmcnt(0)
	s_barrier
	s_cmp_eq_u32 s2, 0x38000
	s_cbranch_scc1 .Lcross_touch_s
	s_add_i32 s34, s2, 0x8000
	s_and_b32 s34, s34, 0x8000
	s_add_i32 s34, s34, 0
	v_lshl_add_u64 v[4:5], v[168:169], 1, v[166:167]
	s_add_i32 s35, s34, s33
	s_mov_b32 s63, m0
	s_mov_b32 m0, s35
	s_nop 0
	global_load_lds_dwordx4 v[4:5], off
	s_mov_b32 m0, s63
	v_lshl_add_u64 v[4:5], v[170:171], 1, v[166:167]
	s_add_i32 s34, s34, s38
	s_mov_b32 s63, m0
	s_mov_b32 m0, s34
	s_nop 0
	global_load_lds_dwordx4 v[4:5], off
	s_mov_b32 m0, s63
	s_add_i32 s34, s35, 0x4000
	s_mov_b32 s63, m0
	s_mov_b32 m0, s34
	s_nop 0
	global_load_lds_dwordx4 v[172:173], off
	s_mov_b32 m0, s63
	v_lshl_add_u64 v[4:5], v[172:173], 0, s[20:21]
	s_add_i32 s34, s35, 0x4400
	s_mov_b32 s35, m0
	s_mov_b32 m0, s34
	s_nop 0
	global_load_lds_dwordx4 v[4:5], off
	s_mov_b32 m0, s35
	s_branch .LBB0_928

; #define LAS __attribute__((address_space(3)))
; DI float fexp2(float x) { return __builtin_amdgcn_exp2f(x); }
; DI int crow(int i, int hh) { return (i & 3) + 8 * (i >> 2) + 4 * hh; }
; DI void cross_unit(Ctx A_, LAS unsigned char* lds, int kvb, int hc, size_t row0, int nrows, int wave, int lane) {
;     ...
;             const LAS unsigned char* buf = lds + (t & 1) * BUF;
;             const LAS unsigned char* kb = buf + hh * 512 + r * 16;
;             f32x16 p0;
; #pragma unroll
;             for (int i = 0; i < 16; ++i) p0[i] = 0.f;
; #pragma unroll
;             for (int d0 = 0; d0 < 16; ++d0) p0 = __builtin_amdgcn_mfma_f32_32x32x16_bf16(*(const LAS bf16x8*)(kb + d0 * 1024), qr[d0], p0, 0, 0, 0);
;             float tm = p0[0];
; #pragma unroll
;             for (int i = 1; i < 16; ++i) tm = fmaxf(tm, p0[i]);
;             tm = fmaxf(tm, __shfl_xor(tm, 32));
;             if (__any(tm > m + RESC_THR)) {
;                 const float mn = fmaxf(m, tm), f = fexp2(m - mn); m = mn; l *= f;
;                 if (hh == 0) wsf[r] = f;
;                 float fr[16];
; #pragma unroll
;                 for (int i = 0; i < 16; ++i) fr[i] = wsf[crow(i, hh)];
; #pragma unroll
;                 for (int nb = 0; nb < 4; ++nb)
; #pragma unroll
;                     for (int i = 0; i < 16; ++i) o[nb][i] *= fr[i];
;             }
.LctC_s:
	v_readfirstlane_b32 s34, v0
	s_lshr_b32 s34, s34, 6
	s_and_b32 s63, s34, 3
	s_lshl_b32 s63, s63, 5
	s_add_i32 s98, s98, s63
	s_lshr_b32 s34, s34, 2
	s_lshl_b32 s34, s34, 8
	s_lshl_b32 s100, s100, 9
	s_add_i32 s100, s100, s34
	s_add_i32 s100, s100, 0x5000
	s_mul_hi_u32 s99, s98, 0x5800
	s_mul_i32 s98, s98, 0x5800
	v_readlane_b32 s34, v255, 9
	v_readlane_b32 s63, v255, 10
	v_and_b32_e32 v206, 63, v0
	v_lshrrev_b32_e32 v207, 1, v206
	s_add_u32 s98, s98, s34
	s_addc_u32 s99, s99, s63
	s_add_u32 s98, s98, s100
	s_addc_u32 s99, s99, 0
	v_mul_u32_u24_e32 v207, 0x5800, v207
	v_and_b32_e32 v206, 1, v206
	v_lshl_or_b32 v206, v206, 7, v207
	s_nop 0
	global_load_dword v207, v206, s[98:99]
.LBB0_928:
	s_and_b32 s34, s2, 0x8000
	s_add_i32 s63, s34, 0
	v_add3_u32 v2, s63, v177, v178
	ds_read_b128 v[4:7], v2
	ds_read_b128 v[8:11], v2 offset:1024
	ds_read_b128 v[236:239], v2 offset:2048
	ds_read_b128 v[240:243], v2 offset:3072
	ds_read_b128 v[244:247], v2 offset:4096
	ds_read_b128 v[248:251], v2 offset:5120
	s_waitcnt lgkmcnt(5)
	v_mfma_f32_32x32x16_bf16 v[82:97], v[4:7], v[98:101], 0
	ds_read_b128 v[4:7], v2 offset:6144
	s_waitcnt lgkmcnt(5)
	v_mfma_f32_32x32x16_bf16 v[82:97], v[8:11], v[158:161], v[82:97]
	ds_read_b128 v[8:11], v2 offset:7168
	s_waitcnt lgkmcnt(5)
	v_mfma_f32_32x32x16_bf16 v[82:97], v[236:239], v[154:157], v[82:97]
	ds_read_b128 v[236:239], v2 offset:8192
	s_waitcnt lgkmcnt(5)
	v_mfma_f32_32x32x16_bf16 v[82:97], v[240:243], v[150:153], v[82:97]
	ds_read_b128 v[240:243], v2 offset:9216
	s_waitcnt lgkmcnt(5)
	v_mfma_f32_32x32x16_bf16 v[82:97], v[244:247], v[146:149], v[82:97]
	ds_read_b128 v[244:247], v2 offset:10240
	s_waitcnt lgkmcnt(5)
	v_mfma_f32_32x32x16_bf16 v[82:97], v[248:251], v[142:145], v[82:97]
	ds_read_b128 v[248:251], v2 offset:11264
	s_waitcnt lgkmcnt(5)
	v_mfma_f32_32x32x16_bf16 v[82:97], v[4:7], v[138:141], v[82:97]
	ds_read_b128 v[4:7], v2 offset:12288
	s_waitcnt lgkmcnt(5)
	v_mfma_f32_32x32x16_bf16 v[82:97], v[8:11], v[134:137], v[82:97]
	ds_read_b128 v[8:11], v2 offset:13312
	s_waitcnt lgkmcnt(5)
	v_mfma_f32_32x32x16_bf16 v[82:97], v[236:239], v[130:133], v[82:97]
	ds_read_b128 v[236:239], v2 offset:14336
	s_waitcnt lgkmcnt(5)
	v_mfma_f32_32x32x16_bf16 v[82:97], v[240:243], v[126:129], v[82:97]
	ds_read_b128 v[240:243], v2 offset:15360
	s_waitcnt lgkmcnt(5)
	v_mfma_f32_32x32x16_bf16 v[82:97], v[244:247], v[122:125], v[82:97]
	s_waitcnt lgkmcnt(4)
	v_mfma_f32_32x32x16_bf16 v[82:97], v[248:251], v[118:121], v[82:97]
	s_waitcnt lgkmcnt(3)
	v_mfma_f32_32x32x16_bf16 v[82:97], v[4:7], v[114:117], v[82:97]
	s_waitcnt lgkmcnt(2)
	v_mfma_f32_32x32x16_bf16 v[82:97], v[8:11], v[110:113], v[82:97]
	s_waitcnt lgkmcnt(1)
	v_mfma_f32_32x32x16_bf16 v[82:97], v[236:239], v[106:109], v[82:97]
	s_waitcnt lgkmcnt(0)
	v_mfma_f32_32x32x16_bf16 v[82:97], v[240:243], v[102:105], v[82:97]
	s_nop 11
	v_max_f32_e32 v2, v83, v83
	v_max_f32_e32 v4, v82, v82
	v_max_f32_e32 v2, v4, v2
	v_max3_f32 v2, v2, v84, v85
	v_max3_f32 v2, v2, v86, v87
	v_max3_f32 v2, v2, v88, v89
	v_max3_f32 v2, v2, v90, v91
	v_max3_f32 v2, v2, v92, v93
	v_max3_f32 v2, v2, v94, v95
	v_max3_f32 v2, v2, v96, v97
	ds_bpermute_b32 v4, v204, v2
	s_waitcnt lgkmcnt(0)
	v_max_f32_e32 v4, v4, v4
	v_max_f32_e32 v2, v2, v4
	v_add_f32_e32 v4, 0x41000000, v183
	v_cmp_gt_f32_e32 vcc, v2, v4
	s_cbranch_vccz .LBB0_932
	v_max_f32_e32 v2, v2, v2
	v_max_f32_e32 v4, v183, v183
	v_max_f32_e32 v2, v4, v2
	v_sub_f32_e32 v4, v183, v2
	v_exp_f32_e32 v4, v4
	s_and_saveexec_b64 s[34:35], s[4:5]
	ds_write_b32 v179, v4
	s_or_b64 exec, exec, s[34:35]
	v_add_u32_e32 v5, s40, v162
	ds_read_b128 v[6:9], v5 offset:96
	ds_read_b128 v[10:13], v5 offset:64
	ds_read_b128 v[14:17], v5 offset:32
	ds_read_b128 v[184:187], v5
	v_mul_f32_e32 v163, v163, v4
	s_waitcnt lgkmcnt(3)
	v_pk_mul_f32 v[30:31], v[30:31], v[6:7]
	s_waitcnt lgkmcnt(2)
	v_pk_mul_f32 v[26:27], v[26:27], v[10:11]
	s_waitcnt lgkmcnt(1)
	v_pk_mul_f32 v[22:23], v[22:23], v[14:15]
	v_pk_mul_f32 v[32:33], v[32:33], v[8:9]
	v_pk_mul_f32 v[28:29], v[28:29], v[12:13]
	v_pk_mul_f32 v[24:25], v[24:25], v[16:17]
	s_waitcnt lgkmcnt(0)
	v_pk_mul_f32 v[20:21], v[20:21], v[186:187]
	v_pk_mul_f32 v[18:19], v[18:19], v[184:185]
	v_pk_mul_f32 v[46:47], v[46:47], v[6:7]
	v_pk_mul_f32 v[42:43], v[42:43], v[10:11]
	v_pk_mul_f32 v[38:39], v[38:39], v[14:15]
	v_pk_mul_f32 v[48:49], v[48:49], v[8:9]
	v_pk_mul_f32 v[44:45], v[44:45], v[12:13]
	v_pk_mul_f32 v[40:41], v[40:41], v[16:17]
	v_pk_mul_f32 v[36:37], v[36:37], v[186:187]
	v_pk_mul_f32 v[34:35], v[34:35], v[184:185]
	v_pk_mul_f32 v[62:63], v[62:63], v[6:7]
	v_pk_mul_f32 v[58:59], v[58:59], v[10:11]
	v_pk_mul_f32 v[54:55], v[54:55], v[14:15]
	v_pk_mul_f32 v[64:65], v[64:65], v[8:9]
	v_pk_mul_f32 v[60:61], v[60:61], v[12:13]
	v_pk_mul_f32 v[56:57], v[56:57], v[16:17]
	v_pk_mul_f32 v[52:53], v[52:53], v[186:187]
	v_pk_mul_f32 v[50:51], v[50:51], v[184:185]
	v_pk_mul_f32 v[78:79], v[78:79], v[6:7]
	v_pk_mul_f32 v[74:75], v[74:75], v[10:11]
	v_pk_mul_f32 v[70:71], v[70:71], v[14:15]
	v_pk_mul_f32 v[80:81], v[80:81], v[8:9]
	v_pk_mul_f32 v[76:77], v[76:77], v[12:13]
	v_pk_mul_f32 v[72:73], v[72:73], v[16:17]
	v_pk_mul_f32 v[68:69], v[68:69], v[186:187]
	v_pk_mul_f32 v[66:67], v[66:67], v[184:185]
	s_branch .LBB0_933

; __global__ void __launch_bounds__(512, 2) fwd(Args args) {
	.amdhsa_kernel _Z3fwd4Args
		.amdhsa_group_segment_fixed_size 0
		.amdhsa_private_segment_fixed_size 0
		.amdhsa_kernarg_size 480
		.amdhsa_user_sgpr_count 2
		.amdhsa_user_sgpr_dispatch_ptr 0
		.amdhsa_user_sgpr_queue_ptr 0
		.amdhsa_user_sgpr_kernarg_segment_ptr 1
		.amdhsa_user_sgpr_dispatch_id 0
		.amdhsa_user_sgpr_kernarg_preload_length 0
		.amdhsa_user_sgpr_kernarg_preload_offset 0
		.amdhsa_user_sgpr_private_segment_size 0
		.amdhsa_uses_dynamic_stack 0
		.amdhsa_enable_private_segment 0
		.amdhsa_system_sgpr_workgroup_id_x 1
		.amdhsa_system_sgpr_workgroup_id_y 0
		.amdhsa_system_sgpr_workgroup_id_z 0
		.amdhsa_system_sgpr_workgroup_info 0
		.amdhsa_system_vgpr_workitem_id 0
		.amdhsa_next_free_vgpr 256
		.amdhsa_next_free_sgpr 102
		.amdhsa_accum_offset 256
		.amdhsa_reserve_vcc 1
		.amdhsa_float_round_mode_32 0
		.amdhsa_float_round_mode_16_64 0
		.amdhsa_float_denorm_mode_32 3
		.amdhsa_float_denorm_mode_16_64 3
		.amdhsa_dx10_clamp 1
		.amdhsa_ieee_mode 1
		.amdhsa_fp16_overflow 0
		.amdhsa_tg_split 0
		.amdhsa_exception_fp_ieee_invalid_op 0
		.amdhsa_exception_fp_denorm_src 0
		.amdhsa_exception_fp_ieee_div_zero 0
		.amdhsa_exception_fp_ieee_overflow 0
		.amdhsa_exception_fp_ieee_underflow 0
		.amdhsa_exception_fp_ieee_inexact 0
		.amdhsa_exception_int_div_zero 0
	.end_amdhsa_kernel

; __global__ void __launch_bounds__(512, 2) fwd(Args args) {
amdhsa.kernels:
  - .agpr_count:     0
    .args:
      - .offset:         0
        .size:           224
        .value_kind:     by_value
      - .offset:         224
        .size:           4
        .value_kind:     hidden_block_count_x
      - .offset:         228
        .size:           4
        .value_kind:     hidden_block_count_y
      - .offset:         232
        .size:           4
        .value_kind:     hidden_block_count_z
      - .offset:         236
        .size:           2
        .value_kind:     hidden_group_size_x
      - .offset:         238
        .size:           2
        .value_kind:     hidden_group_size_y
      - .offset:         240
        .size:           2
        .value_kind:     hidden_group_size_z
      - .offset:         242
        .size:           2
        .value_kind:     hidden_remainder_x
      - .offset:         244
        .size:           2
        .value_kind:     hidden_remainder_y
      - .offset:         246
        .size:           2
        .value_kind:     hidden_remainder_z
      - .offset:         264
        .size:           8
        .value_kind:     hidden_global_offset_x
      - .offset:         272
        .size:           8
        .value_kind:     hidden_global_offset_y
      - .offset:         280
        .size:           8
        .value_kind:     hidden_global_offset_z
      - .offset:         288
        .size:           2
        .value_kind:     hidden_grid_dims
      - .offset:         344
        .size:           4
        .value_kind:     hidden_dynamic_lds_size
    .group_segment_fixed_size: 0
    .kernarg_segment_align: 8
    .kernarg_segment_size: 480
    .language:       OpenCL C
    .language_version:
      - 2
      - 0
    .max_flat_workgroup_size: 512
    .name:           _Z3fwd4Args
    .private_segment_fixed_size: 0
    .sgpr_count:     108
    .sgpr_spill_count: 129
    .symbol:         _Z3fwd4Args.kd
    .uniform_work_group_size: 1
    .uses_dynamic_stack: false
    .vgpr_count:     256
    .vgpr_spill_count: 0
    .wavefront_size: 64
